# PREP weight transpose: descriptor fields fetched once, the four row-group loads of a 64x64 tile issued back to back
# speedup vs baseline: 1.0136x; 1.0136x over previous
.LBB0_1315:
	v_lshlrev_b32_sdwa v2, v215, v9 dst_sel:DWORD dst_unused:UNUSED_PAD src0_sel:DWORD src1_sel:BYTE_0
	v_lshrrev_b32_sdwa v13, v214, v9 dst_sel:DWORD dst_unused:UNUSED_PAD src0_sel:DWORD src1_sel:BYTE_0
	v_and_b32_e32 v20, 48, v2
	v_mul_u32_u24_e32 v2, 0x104, v13
	v_lshlrev_b32_e32 v3, 2, v20
	v_add3_u32 v21, v222, v2, v3
	s_waitcnt lgkmcnt(0)
	s_barrier
	ds_read2_b32 v[2:3], v21 offset1:1
	ds_read2_b32 v[6:7], v21 offset0:8 offset1:9
	ds_read2_b32 v[4:5], v21 offset0:2 offset1:3
	ds_read2_b32 v[8:9], v21 offset0:10 offset1:11
	ds_read2_b32 v[14:15], v21 offset0:4 offset1:5
	ds_read2_b32 v[16:17], v21 offset0:12 offset1:13
	ds_read2_b32 v[18:19], v21 offset0:6 offset1:7
	s_waitcnt lgkmcnt(4)
	s_waitcnt lgkmcnt(2)
	s_waitcnt lgkmcnt(0)
	v_mov_b32_e32 v28, v3
	v_mov_b32_e32 v3, v4
	v_mov_b32_e32 v26, v5
	v_mov_b32_e32 v4, v14
	v_cvt_pk_bf16_f32 v5, v18, v19
	v_cvt_pk_bf16_f32 v4, v4, v15
	ds_read2_b32 v[14:15], v21 offset0:14 offset1:15
	s_waitcnt lgkmcnt(0)
	v_mov_b32_e32 v25, v7
	v_mov_b32_e32 v7, v8
	v_mov_b32_e32 v23, v9
	v_mov_b32_e32 v8, v16
	v_mov_b32_e32 v9, v14
	v_cvt_pk_bf16_f32 v9, v9, v15
	v_cvt_pk_bf16_f32 v8, v8, v17
	v_or_b32_e32 v0, v13, v0
	v_ashrrev_i32_e32 v13, 31, v12
	v_cvt_pk_bf16_f32 v3, v3, v26
	v_cvt_pk_bf16_f32 v2, v2, v28
	v_cvt_pk_bf16_f32 v7, v7, v23
	v_cvt_pk_bf16_f32 v6, v6, v25
	v_mad_i64_i32 v[10:11], s[4:5], v44, v0, 0
	v_lshl_add_u64 v[10:11], v[10:11], 1, v[42:43]
	v_lshl_add_u64 v[10:11], v[12:13], 1, v[10:11]
	v_lshlrev_b32_e32 v0, 1, v20
	v_lshl_add_u64 v[10:11], v[10:11], 0, v[0:1]
	global_store_dwordx4 v[10:11], v[2:5], off
	global_store_dwordx4 v[10:11], v[6:9], off offset:16
	s_barrier

.LBB0_1327:
	v_readlane_b32 s4, v251, 2
	v_lshlrev_b64 v[2:3], 5, v[2:3]
	v_readlane_b32 s5, v251, 3
	s_waitcnt vmcnt(2)
	v_mov_b32_e32 v9, v163
	v_sub_u32_e32 v4, 0, v0
	s_waitcnt vmcnt(1)
	v_lshl_add_u64 v[10:11], s[4:5], 0, v[2:3]
	global_load_dwordx3 v[6:8], v[10:11], off offset:684
	global_load_dwordx4 v[40:43], v[10:11], off offset:664
	global_load_dword v44, v[10:11], off offset:680
	v_max_i32_e32 v4, v0, v4
	s_waitcnt vmcnt(0)
	v_ashrrev_i32_e32 v3, 6, v7
	v_sub_u32_e32 v5, 0, v3
	v_max_i32_e32 v5, v3, v5
	v_cvt_f32_u32_e32 v7, v5
	s_waitcnt lgkmcnt(0)
	v_sub_u32_e32 v12, 0, v5
	v_xor_b32_e32 v2, v0, v3
	v_ashrrev_i32_e32 v2, 31, v2
	v_rcp_iflag_f32_e32 v7, v7
	s_nop 0
	v_mul_f32_e32 v7, 0x4f7ffffe, v7
	v_cvt_u32_f32_e32 v7, v7
	v_mul_lo_u32 v12, v12, v7
	v_mul_hi_u32 v12, v7, v12
	v_add_u32_e32 v7, v7, v12
	v_mul_hi_u32 v7, v4, v7
	v_mul_lo_u32 v12, v7, v5
	v_sub_u32_e32 v4, v4, v12
	v_cmp_ge_u32_e32 vcc, v4, v5
	v_add_u32_e32 v12, 1, v7
	s_nop 0
	v_cndmask_b32_e32 v7, v7, v12, vcc
	v_sub_u32_e32 v12, v4, v5
	v_cndmask_b32_e32 v4, v4, v12, vcc
	v_cmp_ge_u32_e32 vcc, v4, v5
	v_add_u32_e32 v4, 1, v7
	s_nop 0
	v_cndmask_b32_e32 v4, v7, v4, vcc
	v_xor_b32_e32 v4, v4, v2
	v_sub_u32_e32 v2, v4, v2
	v_mul_lo_u32 v3, v2, v3
	v_sub_u32_e32 v3, v0, v3
	v_lshlrev_b32_e32 v0, 6, v3
	v_lshlrev_b32_sdwa v4, v214, v9 dst_sel:DWORD dst_unused:UNUSED_PAD src0_sel:DWORD src1_sel:BYTE_0
	v_lshlrev_b32_e32 v3, 5, v3
	v_bfe_i32 v7, v9, 3, 1
	v_and_b32_e32 v18, 60, v4
	v_and_or_b32 v5, v4, 28, v3
	v_and_b32_e32 v7, 0xb00, v7
	v_or_b32_e32 v14, v18, v0
	v_add_u32_e32 v7, v5, v7
	v_lshlrev_b32_e32 v5, 7, v9
	s_movk_i32 s6, 0x41c
	v_bitop3_b32 v4, v4, s6, v5 bitop3:0xc8
	v_add_u32_e32 v15, v4, v3
	v_cmp_eq_u32_e32 vcc, 1, v8
	v_lshlrev_b32_e32 v12, 6, v2
	v_lshrrev_b32_sdwa v13, v215, v9 dst_sel:DWORD dst_unused:UNUSED_PAD src0_sel:DWORD src1_sel:BYTE_0
	v_cndmask_b32_e32 v16, v14, v15, vcc
	v_cmp_eq_u32_e32 vcc, 2, v8
	v_or_b32_e32 v20, v13, v12
	v_mul_u32_u24_e32 v21, 0x41, v18
	v_cndmask_b32_e32 v16, v16, v7, vcc
	v_cmp_lt_i32_e32 vcc, v14, v6
	v_mad_i64_i32 v[22:23], s[6:7], v20, v6, 0
	v_ashrrev_i32_e32 v17, 31, v16
	v_lshlrev_b32_e32 v24, 6, v6
	v_mov_b32_e32 v25, 0
	v_lshl_add_u64 v[22:23], v[22:23], 2, v[40:41]
	v_lshl_add_u64 v[22:23], v[16:17], 2, v[22:23]
	v_lshl_add_u64 v[26:27], v[22:23], 0, v[24:25]
	v_lshl_add_u64 v[28:29], v[26:27], 0, v[24:25]
	v_lshl_add_u64 v[30:31], v[28:29], 0, v[24:25]
	v_mov_b32_e32 v2, 0
	v_mov_b32_e32 v3, 0
	v_mov_b32_e32 v4, 0
	v_mov_b32_e32 v5, 0
	v_mov_b32_e32 v32, 0
	v_mov_b32_e32 v33, 0
	v_mov_b32_e32 v34, 0
	v_mov_b32_e32 v35, 0
	v_mov_b32_e32 v36, 0
	v_mov_b32_e32 v37, 0
	v_mov_b32_e32 v38, 0
	v_mov_b32_e32 v39, 0
	v_mov_b32_e32 v46, 0
	v_mov_b32_e32 v47, 0
	v_mov_b32_e32 v48, 0
	v_mov_b32_e32 v49, 0
	s_and_saveexec_b64 s[4:5], vcc
	global_load_dwordx4 v[2:5], v[22:23], off nt
	global_load_dwordx4 v[32:35], v[26:27], off nt
	global_load_dwordx4 v[36:39], v[28:29], off nt
	global_load_dwordx4 v[46:49], v[30:31], off nt
	s_or_b64 exec, exec, s[4:5]
	v_lshlrev_b32_e32 v17, 2, v13
	v_lshlrev_b32_e32 v16, 2, v21
	v_add3_u32 v18, v222, v17, v16
	v_add3_u32 v19, v222, v16, v17
	s_waitcnt vmcnt(3)
	ds_write_b32 v18, v2
	ds_write2_b32 v19, v3, v4 offset0:65 offset1:130
	ds_write_b32 v19, v5 offset:780
	s_waitcnt vmcnt(2)
	ds_write_b32 v18, v32 offset:64
	ds_write2_b32 v19, v33, v34 offset0:81 offset1:146
	ds_write_b32 v19, v35 offset:844
	s_waitcnt vmcnt(1)
	ds_write_b32 v18, v36 offset:128
	ds_write2_b32 v19, v37, v38 offset0:97 offset1:162
	ds_write_b32 v19, v39 offset:908
	s_waitcnt vmcnt(0)
	ds_write_b32 v18, v46 offset:192
	ds_write2_b32 v19, v47, v48 offset0:113 offset1:178
	ds_write_b32 v19, v49 offset:972
	s_branch .LBB0_1315
